# v22 plus MLA final-tile QK LDS reads pipelined 5 deep with counted lgkmcnt waits
# speedup vs baseline: 1.0024x; 1.0005x over previous
.LBB0_571:
	v_readlane_b32 s10, v254, 61
	s_cmp_gt_i32 s7, s14
	s_mov_b32 s24, s10
	v_readlane_b32 s11, v254, 62
	s_cbranch_scc1 .LBB0_584
	s_add_i32 s3, 0, 0x10000
	v_lshl_add_u32 v108, v215, 7, s3
	s_or_b32 s3, s7, 63
	s_cmp_le_i32 s3, s6
	v_add_u32_e32 v180, v226, v225
	v_xad_u32 v181, v225, 32, v226
	v_xad_u32 v182, v225, 64, v226
	ds_read_b128 v[100:103], v180 offset:32768
	ds_read_b128 v[236:239], v180 offset:40960
	ds_read_b128 v[240:243], v181 offset:32768
	ds_read_b128 v[244:247], v181 offset:40960
	ds_read_b128 v[248:251], v182 offset:32768
	s_waitcnt lgkmcnt(4)
	v_mfma_f32_32x32x16_bf16 v[84:99], v[100:103], v[176:179], v[68:83]
	ds_read_b128 v[100:103], v182 offset:40960
	v_xad_u32 v183, v225, s26, v226
	s_waitcnt lgkmcnt(4)
	v_mfma_f32_32x32x16_bf16 v[68:83], v[236:239], v[176:179], v[68:83]
	ds_read_b128 v[236:239], v183 offset:32768
	s_waitcnt lgkmcnt(4)
	v_mfma_f32_32x32x16_bf16 v[84:99], v[240:243], v[172:175], v[84:99]
	ds_read_b128 v[240:243], v183 offset:40960
	v_xad_u32 v180, v225, s57, v226
	s_waitcnt lgkmcnt(4)
	v_mfma_f32_32x32x16_bf16 v[68:83], v[244:247], v[172:175], v[68:83]
	ds_read_b128 v[244:247], v180 offset:32768
	s_waitcnt lgkmcnt(4)
	v_mfma_f32_32x32x16_bf16 v[84:99], v[248:251], v[168:171], v[84:99]
	ds_read_b128 v[248:251], v180 offset:40960
	v_xad_u32 v181, v225, s90, v226
	s_waitcnt lgkmcnt(4)
	v_mfma_f32_32x32x16_bf16 v[68:83], v[100:103], v[168:171], v[68:83]
	ds_read_b128 v[100:103], v181 offset:32768
	s_waitcnt lgkmcnt(4)
	v_mfma_f32_32x32x16_bf16 v[84:99], v[236:239], v[164:167], v[84:99]
	ds_read_b128 v[236:239], v181 offset:40960
	v_xad_u32 v182, v225, s56, v226
	s_waitcnt lgkmcnt(4)
	v_mfma_f32_32x32x16_bf16 v[68:83], v[240:243], v[164:167], v[68:83]
	ds_read_b128 v[240:243], v182 offset:32768
	s_waitcnt lgkmcnt(4)
	v_mfma_f32_32x32x16_bf16 v[84:99], v[244:247], v[160:163], v[84:99]
	ds_read_b128 v[244:247], v182 offset:40960
	v_xad_u32 v183, v225, s74, v226
	s_waitcnt lgkmcnt(4)
	v_mfma_f32_32x32x16_bf16 v[68:83], v[248:251], v[160:163], v[68:83]
	ds_read_b128 v[248:251], v183 offset:32768
	s_waitcnt lgkmcnt(4)
	v_mfma_f32_32x32x16_bf16 v[84:99], v[100:103], v[156:159], v[84:99]
	ds_read_b128 v[100:103], v183 offset:40960
	v_xad_u32 v180, v2, v224, v108
	s_waitcnt lgkmcnt(4)
	v_mfma_f32_32x32x16_bf16 v[68:83], v[236:239], v[156:159], v[68:83]
	ds_read_b128 v[236:239], v180
	s_waitcnt lgkmcnt(4)
	v_mfma_f32_32x32x16_bf16 v[84:99], v[240:243], v[152:155], v[84:99]
	ds_read_b128 v[240:243], v180 offset:4096
	v_or_b32_e32 v184, 32, v2
	v_xad_u32 v181, v184, v224, v108
	s_waitcnt lgkmcnt(4)
	v_mfma_f32_32x32x16_bf16 v[68:83], v[244:247], v[152:155], v[68:83]
	ds_read_b128 v[244:247], v181
	s_waitcnt lgkmcnt(4)
	v_mfma_f32_32x32x16_bf16 v[84:99], v[248:251], v[148:151], v[84:99]
	ds_read_b128 v[248:251], v181 offset:4096
	v_or_b32_e32 v184, 64, v2
	v_xad_u32 v182, v184, v224, v108
	s_waitcnt lgkmcnt(4)
	v_mfma_f32_32x32x16_bf16 v[68:83], v[100:103], v[148:151], v[68:83]
	ds_read_b128 v[100:103], v182
	s_waitcnt lgkmcnt(4)
	v_mfma_f32_32x32x16_bf16 v[84:99], v[236:239], v[144:147], v[84:99]
	ds_read_b128 v[236:239], v182 offset:4096
	v_or_b32_e32 v184, 0x60, v2
	v_xad_u32 v183, v184, v224, v108
	s_waitcnt lgkmcnt(4)
	v_mfma_f32_32x32x16_bf16 v[68:83], v[240:243], v[144:147], v[68:83]
	ds_read_b128 v[240:243], v183
	s_waitcnt lgkmcnt(4)
	v_mfma_f32_32x32x16_bf16 v[84:99], v[244:247], v[140:143], v[84:99]
	ds_read_b128 v[244:247], v183 offset:4096
	s_waitcnt lgkmcnt(4)
	v_mfma_f32_32x32x16_bf16 v[68:83], v[248:251], v[140:143], v[68:83]
	s_waitcnt lgkmcnt(3)
	v_mfma_f32_32x32x16_bf16 v[84:99], v[100:103], v[136:139], v[84:99]
	s_waitcnt lgkmcnt(2)
	v_mfma_f32_32x32x16_bf16 v[68:83], v[236:239], v[136:139], v[68:83]
	s_waitcnt lgkmcnt(1)
	v_mfma_f32_32x32x16_bf16 v[84:99], v[240:243], v[132:135], v[84:99]
	s_waitcnt lgkmcnt(0)
	v_mfma_f32_32x32x16_bf16 v[68:83], v[244:247], v[132:135], v[68:83]
	s_nop 1
	s_cbranch_scc1 .LBB0_574
	v_sub_u32_e32 v2, v223, v216
	v_subrev_u32_e32 v2, s7, v2
	v_cmp_gt_u32_e32 vcc, 2.0, v2
	v_add_u32_e32 v100, 0xbfffffe0, v2
	s_nop 4
	v_cndmask_b32_e32 v84, v212, v84, vcc
	v_cmp_lt_u32_e32 vcc, s82, v100
	v_add_u32_e32 v100, 0xbfffffff, v2
	s_nop 0
	v_cndmask_b32_e32 v68, v212, v68, vcc
	v_cmp_lt_u32_e32 vcc, s82, v100
	v_add_u32_e32 v100, 0xbfffffdf, v2
	s_nop 0
	v_cndmask_b32_e32 v85, v212, v85, vcc
	v_cmp_lt_u32_e32 vcc, s82, v100
	v_add_u32_e32 v100, 0xbffffffe, v2
	s_nop 0
	v_cndmask_b32_e32 v69, v212, v69, vcc
	v_cmp_lt_u32_e32 vcc, s82, v100
	v_add_u32_e32 v100, 0xbfffffde, v2
	s_nop 0
	v_cndmask_b32_e32 v86, v212, v86, vcc
	v_cmp_lt_u32_e32 vcc, s82, v100
	v_add_u32_e32 v100, 0xbffffffd, v2
	s_nop 0
	v_cndmask_b32_e32 v70, v212, v70, vcc
	v_cmp_lt_u32_e32 vcc, s82, v100
	v_add_u32_e32 v100, 0xbfffffdd, v2
	s_nop 0
	v_cndmask_b32_e32 v87, v212, v87, vcc
	v_cmp_lt_u32_e32 vcc, s82, v100
	v_add_u32_e32 v100, 0xbffffff8, v2
	s_nop 0
	v_cndmask_b32_e32 v71, v212, v71, vcc
	v_cmp_lt_u32_e32 vcc, s82, v100
	v_add_u32_e32 v100, 0xbfffffd8, v2
	s_nop 0
	v_cndmask_b32_e32 v88, v212, v88, vcc
	v_cmp_lt_u32_e32 vcc, s82, v100
	v_add_u32_e32 v100, 0xbffffff7, v2
	s_nop 0
	v_cndmask_b32_e32 v72, v212, v72, vcc
	v_cmp_lt_u32_e32 vcc, s82, v100
	v_add_u32_e32 v100, 0xbfffffd7, v2
	s_nop 0
	v_cndmask_b32_e32 v89, v212, v89, vcc
	v_cmp_lt_u32_e32 vcc, s82, v100
	v_add_u32_e32 v100, 0xbffffff6, v2
	s_nop 0
	v_cndmask_b32_e32 v73, v212, v73, vcc
	v_cmp_lt_u32_e32 vcc, s82, v100
	v_add_u32_e32 v100, 0xbfffffd6, v2
	s_nop 0
	v_cndmask_b32_e32 v90, v212, v90, vcc
	v_cmp_lt_u32_e32 vcc, s82, v100
	v_add_u32_e32 v100, 0xbffffff5, v2
	s_nop 0
	v_cndmask_b32_e32 v74, v212, v74, vcc
	v_cmp_lt_u32_e32 vcc, s82, v100
	v_add_u32_e32 v100, 0xbfffffd5, v2
	s_nop 0
	v_cndmask_b32_e32 v91, v212, v91, vcc
	v_cmp_lt_u32_e32 vcc, s82, v100
	v_add_u32_e32 v100, 0xbffffff0, v2
	s_nop 0
	v_cndmask_b32_e32 v75, v212, v75, vcc
	v_cmp_lt_u32_e32 vcc, s82, v100
	v_add_u32_e32 v100, 0xbfffffd0, v2
	s_nop 0
	v_cndmask_b32_e32 v92, v212, v92, vcc
	v_cmp_lt_u32_e32 vcc, s82, v100
	v_add_u32_e32 v100, 0xbfffffef, v2
	s_nop 0
	v_cndmask_b32_e32 v76, v212, v76, vcc
	v_cmp_lt_u32_e32 vcc, s82, v100
	v_add_u32_e32 v100, 0xbfffffcf, v2
	s_nop 0
	v_cndmask_b32_e32 v93, v212, v93, vcc
	v_cmp_lt_u32_e32 vcc, s82, v100
	v_add_u32_e32 v100, 0xbfffffee, v2
	s_nop 0
	v_cndmask_b32_e32 v77, v212, v77, vcc
	v_cmp_lt_u32_e32 vcc, s82, v100
	v_add_u32_e32 v100, 0xbfffffce, v2
	s_nop 0
	v_cndmask_b32_e32 v94, v212, v94, vcc
	v_cmp_lt_u32_e32 vcc, s82, v100
	v_add_u32_e32 v100, 0xbfffffed, v2
	s_nop 0
	v_cndmask_b32_e32 v78, v212, v78, vcc
	v_cmp_lt_u32_e32 vcc, s82, v100
	v_add_u32_e32 v100, 0xbfffffcd, v2
	s_nop 0
	v_cndmask_b32_e32 v95, v212, v95, vcc
	v_cmp_lt_u32_e32 vcc, s82, v100
	v_add_u32_e32 v100, 0xbfffffe8, v2
	s_nop 0
	v_cndmask_b32_e32 v79, v212, v79, vcc
	v_cmp_lt_u32_e32 vcc, s82, v100
	v_add_u32_e32 v100, 0xbfffffc8, v2
	s_nop 0
	v_cndmask_b32_e32 v96, v212, v96, vcc
	v_cmp_lt_u32_e32 vcc, s82, v100
	v_add_u32_e32 v100, 0xbfffffe7, v2
	s_nop 0
	v_cndmask_b32_e32 v80, v212, v80, vcc
	v_cmp_lt_u32_e32 vcc, s82, v100
	v_add_u32_e32 v100, 0xbfffffc7, v2
	s_nop 0
	v_cndmask_b32_e32 v97, v212, v97, vcc
	v_cmp_lt_u32_e32 vcc, s82, v100
	v_add_u32_e32 v100, 0xbfffffe6, v2
	s_nop 0
	v_cndmask_b32_e32 v81, v212, v81, vcc
	v_cmp_lt_u32_e32 vcc, s82, v100
	v_add_u32_e32 v100, 0xbfffffc6, v2
	s_nop 0
	v_cndmask_b32_e32 v98, v212, v98, vcc
	v_cmp_lt_u32_e32 vcc, s82, v100
	v_add_u32_e32 v100, 0xbfffffe5, v2
	v_add_u32_e32 v2, 0xbfffffc5, v2
	v_cndmask_b32_e32 v82, v212, v82, vcc
	v_cmp_lt_u32_e32 vcc, s82, v100
	s_nop 1
	v_cndmask_b32_e32 v99, v212, v99, vcc
	v_cmp_lt_u32_e32 vcc, s82, v2
	s_nop 1
	v_cndmask_b32_e32 v83, v212, v83, vcc
